# v28 plus P11 weight conversions run early: w_up at tail of P8 interval, w_dn w_pg w_pl at tail of P10 interval
# speedup vs baseline: 1.0040x; 1.0022x over previous
_Z8mega_fwd4Args:
	s_mov_b32 s99, 0
	s_mov_b32 s98, 0
	s_mov_b32 s96, s2
	v_readfirstlane_b32 s2, v0
	s_lshr_b32 s2, s2, 6
	v_mbcnt_lo_u32_b32 v3, -1, 0
	v_mbcnt_hi_u32_b32 v3, -1, v3
	s_load_dword s15, s[0:1], 0xf8
	s_load_dwordx2 s[94:95], s[0:1], 0xe0
	s_load_dwordx4 s[4:7], s[0:1], 0xe8
	s_load_dwordx8 s[68:75], s[0:1], 0xc0
	v_writelane_b32 v254, s2, 0
	s_add_u32 s2, s0, 0xf8
	s_addc_u32 s3, s1, 0
	s_waitcnt lgkmcnt(0)
	v_writelane_b32 v254, s4, 1
	s_mov_b32 s10, s96
	s_nop 0
	v_writelane_b32 v254, s5, 2
	v_writelane_b32 v254, s6, 3
	v_writelane_b32 v254, s7, 4
	v_writelane_b32 v254, s2, 5
	s_nop 1
	v_writelane_b32 v254, s3, 6
	s_and_b32 s3, s15, 7
	s_mov_b32 s2, 0
	s_cmp_lg_u32 s3, 0
	s_cbranch_scc1 .LBB0_2
	s_ashr_i32 s4, s96, 31
	s_lshr_b32 s4, s4, 29
	s_add_i32 s4, s96, s4
	s_and_b32 s5, s4, -8
	s_ashr_i32 s3, s15, 3
	s_sub_i32 s5, s96, s5
	s_mul_i32 s3, s3, s5
	s_ashr_i32 s4, s4, 3
	s_add_i32 s10, s3, s4

.LBB0_686:
	s_cmp_eq_u32 s99, 0
	s_cbranch_scc0 .Lmy_c11_norm686
	s_mov_b32 s99, 1
	v_writelane_b32 v255, s0, 10
	v_writelane_b32 v255, s1, 11
	v_writelane_b32 v255, s2, 12
	v_writelane_b32 v255, s3, 13
	v_writelane_b32 v255, s4, 14
	v_writelane_b32 v255, s5, 15
	v_writelane_b32 v255, s6, 16
	v_writelane_b32 v255, s7, 17
	v_writelane_b32 v255, s12, 18
	v_writelane_b32 v255, s13, 19
	v_writelane_b32 v255, s16, 20
	v_writelane_b32 v255, s17, 21
	v_writelane_b32 v255, s18, 22
	v_writelane_b32 v255, s19, 23
	v_writelane_b32 v255, s21, 24
	v_writelane_b32 v255, s23, 25
	v_writelane_b32 v255, s24, 26
	v_writelane_b32 v255, s25, 27
	v_writelane_b32 v255, s26, 28
	v_writelane_b32 v255, s27, 29
	v_writelane_b32 v255, s28, 30
	v_writelane_b32 v255, s29, 31
	v_writelane_b32 v255, s30, 32
	v_writelane_b32 v255, s31, 33
	v_writelane_b32 v255, s33, 34
	v_writelane_b32 v255, s54, 35
	v_writelane_b32 v255, s64, 36
	s_mov_b64 s[0:1], -1
	s_branch .LBB0_819

.LBB0_765:
	s_cmp_eq_u32 s99, 2
	s_cbranch_scc0 .Lmy_c11_norm765
	s_mov_b32 s99, 3
	v_writelane_b32 v255, s0, 10
	v_writelane_b32 v255, s1, 11
	v_writelane_b32 v255, s2, 12
	v_writelane_b32 v255, s3, 13
	v_writelane_b32 v255, s4, 14
	v_writelane_b32 v255, s5, 15
	v_writelane_b32 v255, s6, 16
	v_writelane_b32 v255, s7, 17
	v_writelane_b32 v255, s12, 18
	v_writelane_b32 v255, s16, 19
	v_writelane_b32 v255, s17, 20
	v_writelane_b32 v255, s18, 21
	v_writelane_b32 v255, s19, 22
	v_writelane_b32 v255, s21, 23
	v_writelane_b32 v255, s23, 24
	v_writelane_b32 v255, s24, 25
	v_writelane_b32 v255, s25, 26
	v_writelane_b32 v255, s26, 27
	v_writelane_b32 v255, s27, 28
	v_writelane_b32 v255, s28, 29
	v_writelane_b32 v255, s29, 30
	v_writelane_b32 v255, s30, 31
	v_writelane_b32 v255, s31, 32
	v_writelane_b32 v255, s33, 33
	v_writelane_b32 v255, s54, 34
	v_writelane_b32 v255, s64, 35
	s_mov_b64 s[0:1], -1
	s_branch .LBB0_819

.LBB0_819:
	v_readlane_b32 s4, v254, 1
	s_cmp_lt_i32 s4, 12
	s_cselect_b64 s[2:3], -1, 0
	s_and_b64 s[0:1], s[2:3], s[0:1]
	s_add_u32 s54, s94, 0x10100000
	s_addc_u32 s64, s95, 0
	s_add_u32 s4, s94, 0x1c100000
	v_readlane_b32 s5, v254, 2
	v_readlane_b32 s6, v254, 3
	v_readlane_b32 s7, v254, 4
	v_writelane_b32 v254, s4, 41
	s_addc_u32 s4, s95, 0
	v_writelane_b32 v255, s4, 3
	s_add_u32 s4, s94, 0x22100000
	s_addc_u32 s33, s95, 0
	v_writelane_b32 v254, s4, 0
	s_add_u32 s4, s94, 0x24100000
	v_writelane_b32 v254, s4, 42
	s_addc_u32 s4, s95, 0
	v_writelane_b32 v254, s4, 40
	s_andn2_b64 vcc, exec, s[0:1]
	s_cbranch_vccnz .LBB0_849
	s_cmp_eq_u32 s99, 4
	s_cbranch_scc0 .Lmy_c11_run
	v_mbcnt_lo_u32_b32 v24, -1, 0
	v_mbcnt_hi_u32_b32 v24, -1, v24
	s_branch .LBB0_842
.Lmy_c11_run:
	v_readlane_b32 s0, v254, 54
	s_cmp_gt_i32 s0, 0xbfff
	v_mbcnt_lo_u32_b32 v24, -1, 0
	v_mbcnt_hi_u32_b32 v24, -1, v24
	s_mul_hi_i32 s6, s0, 0x2aaaaaab
	v_ashrrev_i32_e32 v4, 5, v24
	v_and_b32_e32 v0, 31, v24
	v_ashrrev_i32_e32 v2, 3, v24
	v_lshlrev_b32_e32 v1, 3, v24
	v_readlane_b32 s1, v254, 55
	s_cbranch_scc1 .LBB0_827
	s_cmp_lg_u32 s99, 1
	s_cbranch_scc1 .LBB0_827
	v_readlane_b32 s16, v254, 23
	s_lshr_b32 s0, s6, 31
	s_ashr_i32 s1, s6, 7
	v_readlane_b32 s17, v254, 24
	v_readlane_b32 s18, v254, 25
	v_readlane_b32 s19, v254, 26
	v_readlane_b32 s20, v254, 27
	v_readlane_b32 s21, v254, 28
	v_readlane_b32 s22, v254, 29
	v_readlane_b32 s23, v254, 30
	v_readlane_b32 s24, v254, 31
	v_readlane_b32 s25, v254, 32
	v_readlane_b32 s26, v254, 33
	v_readlane_b32 s27, v254, 34
	s_add_i32 s1, s1, s0
	v_readlane_b32 s28, v254, 35
	v_readlane_b32 s29, v254, 36
	v_readlane_b32 s30, v254, 37
	v_readlane_b32 s31, v254, 38
	s_mov_b64 s[16:17], s[20:21]
	s_lshl_b32 s4, s1, 6
	s_mul_i32 s5, s1, 0x600000
	s_mov_b64 s[18:19], s[22:23]
	s_mul_hi_i32 s4, s4, 0x18000
	s_add_u32 s7, s18, s5
	s_mulk_i32 s1, 0x300
	v_readlane_b32 s10, v254, 54
	s_addc_u32 s8, s19, s4
	s_sub_i32 s1, s10, s1
	s_lshl_b32 s4, s1, 5
	s_ashr_i32 s5, s4, 31
	s_lshl_b64 s[4:5], s[4:5], 2
	s_add_u32 s4, s7, s4
	s_addc_u32 s5, s8, s5
	v_mov_b32_e32 v7, 0
	v_lshlrev_b32_e32 v6, 2, v0
	s_mov_b32 s0, 0x18000
	v_lshl_add_u64 v[18:19], s[4:5], 0, v[6:7]
	v_add_u32_e32 v3, 2, v4
	v_mad_i64_i32 v[10:11], s[4:5], v3, s0, 0
	v_mad_i64_i32 v[22:23], s[4:5], v3, s0, v[18:19]
	v_add_u32_e32 v3, 4, v4
	v_mad_i64_i32 v[12:13], s[4:5], v3, s0, 0
	v_mad_i64_i32 v[26:27], s[4:5], v3, s0, v[18:19]
	v_add_u32_e32 v3, 6, v4
	v_mad_i64_i32 v[14:15], s[4:5], v3, s0, 0
	v_mad_i64_i32 v[28:29], s[4:5], v3, s0, v[18:19]
	v_add_u32_e32 v3, 8, v4
	v_mad_i64_i32 v[20:21], s[4:5], v4, s0, v[18:19]
	v_mad_i64_i32 v[16:17], s[4:5], v3, s0, 0
	v_mad_i64_i32 v[30:31], s[4:5], v3, s0, v[18:19]
	v_add_u32_e32 v3, 10, v4
	v_add_u32_e32 v5, 12, v4
	v_add_u32_e32 v38, 14, v4
	v_add_u32_e32 v39, 16, v4
	v_mad_i64_i32 v[32:33], s[4:5], v3, s0, v[18:19]
	v_mad_i64_i32 v[34:35], s[4:5], v5, s0, v[18:19]
	v_mad_i64_i32 v[36:37], s[4:5], v38, s0, v[18:19]
	global_load_dword v25, v[20:21], off
	global_load_dword v84, v[22:23], off
	global_load_dword v85, v[26:27], off
	global_load_dword v86, v[28:29], off
	global_load_dword v87, v[30:31], off
	global_load_dword v88, v[32:33], off
	global_load_dword v89, v[34:35], off
	global_load_dword v90, v[36:37], off
	v_mad_i64_i32 v[20:21], s[4:5], v39, s0, v[18:19]
	v_add_u32_e32 v40, 18, v4
	v_add_u32_e32 v41, 20, v4
	v_add_u32_e32 v42, 22, v4
	v_add_u32_e32 v43, 24, v4
	v_add_u32_e32 v44, 26, v4
	v_add_u32_e32 v45, 28, v4
	v_add_u32_e32 v46, 30, v4
	v_add_u32_e32 v47, 32, v4
	v_mad_i64_i32 v[22:23], s[4:5], v40, s0, v[18:19]
	v_mad_i64_i32 v[26:27], s[4:5], v41, s0, v[18:19]
	v_mad_i64_i32 v[28:29], s[4:5], v42, s0, v[18:19]
	v_mad_i64_i32 v[30:31], s[4:5], v43, s0, v[18:19]
	v_mad_i64_i32 v[32:33], s[4:5], v44, s0, v[18:19]
	v_mad_i64_i32 v[34:35], s[4:5], v45, s0, v[18:19]
	v_mad_i64_i32 v[36:37], s[4:5], v46, s0, v[18:19]
	global_load_dword v91, v[20:21], off
	global_load_dword v92, v[22:23], off
	global_load_dword v93, v[26:27], off
	global_load_dword v94, v[28:29], off
	global_load_dword v95, v[30:31], off
	global_load_dword v96, v[32:33], off
	global_load_dword v97, v[34:35], off
	global_load_dword v98, v[36:37], off
	v_mad_i64_i32 v[20:21], s[4:5], v47, s0, v[18:19]
	v_add_u32_e32 v48, 34, v4
	v_add_u32_e32 v49, 36, v4
	v_add_u32_e32 v50, 38, v4
	v_add_u32_e32 v51, 40, v4
	v_add_u32_e32 v52, 42, v4
	v_add_u32_e32 v54, 44, v4
	v_add_u32_e32 v56, 46, v4
	v_add_u32_e32 v58, 48, v4
	v_mad_i64_i32 v[22:23], s[4:5], v48, s0, v[18:19]
	v_mad_i64_i32 v[26:27], s[4:5], v49, s0, v[18:19]
	v_mad_i64_i32 v[28:29], s[4:5], v50, s0, v[18:19]
	v_mad_i64_i32 v[30:31], s[4:5], v51, s0, v[18:19]
	v_mad_i64_i32 v[32:33], s[4:5], v52, s0, v[18:19]
	v_mad_i64_i32 v[34:35], s[4:5], v54, s0, v[18:19]
	v_mad_i64_i32 v[36:37], s[4:5], v56, s0, v[18:19]
	global_load_dword v114, v[20:21], off
	global_load_dword v123, v[22:23], off
	global_load_dword v124, v[26:27], off
	global_load_dword v125, v[28:29], off
	global_load_dword v126, v[30:31], off
	global_load_dword v127, v[32:33], off
	global_load_dword v128, v[34:35], off
	global_load_dword v129, v[36:37], off
	v_mad_i64_i32 v[20:21], s[4:5], v58, s0, v[18:19]
	v_add_u32_e32 v60, 50, v4
	v_add_u32_e32 v62, 52, v4
	v_add_u32_e32 v64, 54, v4
	v_add_u32_e32 v66, 56, v4
	v_add_u32_e32 v68, 58, v4
	v_add_u32_e32 v70, 60, v4
	v_add_u32_e32 v72, 62, v4
	v_mad_i64_i32 v[22:23], s[4:5], v60, s0, v[18:19]
	v_mad_i64_i32 v[26:27], s[4:5], v62, s0, v[18:19]
	v_mad_i64_i32 v[28:29], s[4:5], v64, s0, v[18:19]
	v_mad_i64_i32 v[30:31], s[4:5], v66, s0, v[18:19]
	v_mad_i64_i32 v[32:33], s[4:5], v68, s0, v[18:19]
	v_mad_i64_i32 v[34:35], s[4:5], v70, s0, v[18:19]
	v_mad_i64_i32 v[18:19], s[4:5], v72, s0, v[18:19]
	global_load_dword v138, v[20:21], off
	global_load_dword v139, v[22:23], off
	global_load_dword v140, v[26:27], off
	global_load_dword v141, v[28:29], off
	global_load_dword v142, v[30:31], off
	global_load_dword v143, v[32:33], off
	global_load_dword v144, v[34:35], off
	global_load_dword v145, v[18:19], off
	v_add_u32_e32 v83, s77, v6
	v_and_b32_e32 v6, 56, v1
	v_mad_i64_i32 v[8:9], s[4:5], v4, s0, 0
	v_mad_i64_i32 v[18:19], s[4:5], v3, s0, 0
	v_mad_i64_i32 v[20:21], s[4:5], v5, s0, 0
	v_mad_i64_i32 v[22:23], s[4:5], v38, s0, 0
	v_mad_i64_i32 v[26:27], s[4:5], v39, s0, 0
	v_mad_i64_i32 v[28:29], s[4:5], v40, s0, 0
	v_mad_i64_i32 v[30:31], s[4:5], v41, s0, 0
	v_mad_i64_i32 v[32:33], s[4:5], v42, s0, 0
	v_mad_i64_i32 v[34:35], s[4:5], v43, s0, 0
	v_mad_i64_i32 v[36:37], s[4:5], v44, s0, 0
	v_mad_i64_i32 v[38:39], s[4:5], v45, s0, 0
	v_mad_i64_i32 v[40:41], s[4:5], v46, s0, 0
	v_mad_i64_i32 v[42:43], s[4:5], v47, s0, 0
	v_mad_i64_i32 v[44:45], s[4:5], v48, s0, 0
	v_mad_i64_i32 v[46:47], s[4:5], v49, s0, 0
	v_mad_i64_i32 v[48:49], s[4:5], v50, s0, 0
	v_mad_i64_i32 v[50:51], s[4:5], v51, s0, 0
	v_mad_i64_i32 v[52:53], s[4:5], v52, s0, 0
	v_mad_i64_i32 v[54:55], s[4:5], v54, s0, 0
	v_mad_i64_i32 v[56:57], s[4:5], v56, s0, 0
	v_mad_i64_i32 v[58:59], s[4:5], v58, s0, 0
	v_mad_i64_i32 v[60:61], s[4:5], v60, s0, 0
	v_mad_i64_i32 v[62:63], s[4:5], v62, s0, 0
	v_mad_i64_i32 v[64:65], s[4:5], v64, s0, 0
	v_mad_i64_i32 v[66:67], s[4:5], v66, s0, 0
	v_mad_i64_i32 v[68:69], s[4:5], v68, s0, 0
	v_mad_i64_i32 v[70:71], s[4:5], v70, s0, 0
	v_mad_i64_i32 v[72:73], s[0:1], v72, s0, 0
	v_mul_u32_u24_e32 v3, 0x84, v6
	v_lshlrev_b32_e32 v5, 2, v2
	s_movk_i32 s0, 0x84
	v_add3_u32 v5, s77, v3, v5
	v_ashrrev_i32_e32 v3, 31, v2
	v_mul_lo_u32 v99, v4, s0
	v_lshlrev_b64 v[74:75], 13, v[2:3]
	s_mov_b64 s[0:1], 0x10000
	v_lshl_add_u64 v[76:77], v[74:75], 0, s[0:1]
	s_mov_b64 s[0:1], 0x20000
	v_readlane_b32 s11, v254, 55
	v_lshl_add_u64 v[78:79], v[74:75], 0, s[0:1]
	s_mov_b64 s[0:1], 0x30000
	v_lshl_add_u64 v[80:81], v[74:75], 0, s[0:1]
	s_lshl_b32 s11, s10, 5
	s_lshl_b32 s7, s80, 5
	v_lshlrev_b32_e32 v82, 2, v0
	v_add_u32_e32 v3, v83, v99
	v_lshlrev_b32_e32 v6, 1, v6
	s_movk_i32 s8, 0x7fff
	s_mov_b32 s9, 0xffff0000
	s_mov_b32 s13, s10
	s_mov_b64 s[20:21], s[24:25]
	s_mov_b64 s[22:23], s[26:27]
	s_mov_b64 s[24:25], s[28:29]
	s_mov_b64 s[26:27], s[30:31]
	s_branch .LBB0_823

.LBB0_827:
	s_cmp_eq_u32 s99, 1
	s_cbranch_scc0 .Lmy_c11_norm827
	s_mov_b32 s99, 2
	v_readlane_b32 s0, v255, 10
	v_readlane_b32 s1, v255, 11
	v_readlane_b32 s2, v255, 12
	v_readlane_b32 s3, v255, 13
	v_readlane_b32 s4, v255, 14
	v_readlane_b32 s5, v255, 15
	v_readlane_b32 s6, v255, 16
	v_readlane_b32 s7, v255, 17
	v_readlane_b32 s12, v255, 18
	v_readlane_b32 s13, v255, 19
	v_readlane_b32 s16, v255, 20
	v_readlane_b32 s17, v255, 21
	v_readlane_b32 s18, v255, 22
	v_readlane_b32 s19, v255, 23
	v_readlane_b32 s21, v255, 24
	v_readlane_b32 s23, v255, 25
	v_readlane_b32 s24, v255, 26
	v_readlane_b32 s25, v255, 27
	v_readlane_b32 s26, v255, 28
	v_readlane_b32 s27, v255, 29
	v_readlane_b32 s28, v255, 30
	v_readlane_b32 s29, v255, 31
	v_readlane_b32 s30, v255, 32
	v_readlane_b32 s31, v255, 33
	v_readlane_b32 s33, v255, 34
	v_readlane_b32 s54, v255, 35
	v_readlane_b32 s64, v255, 36
	s_branch .LBB0_686

.LBB0_842:
	s_cmp_eq_u32 s99, 3
	s_cbranch_scc0 .Lmy_c11_norm842
	s_mov_b32 s99, 4
	v_readlane_b32 s0, v255, 10
	v_readlane_b32 s1, v255, 11
	v_readlane_b32 s2, v255, 12
	v_readlane_b32 s3, v255, 13
	v_readlane_b32 s4, v255, 14
	v_readlane_b32 s5, v255, 15
	v_readlane_b32 s6, v255, 16
	v_readlane_b32 s7, v255, 17
	v_readlane_b32 s12, v255, 18
	v_readlane_b32 s16, v255, 19
	v_readlane_b32 s17, v255, 20
	v_readlane_b32 s18, v255, 21
	v_readlane_b32 s19, v255, 22
	v_readlane_b32 s21, v255, 23
	v_readlane_b32 s23, v255, 24
	v_readlane_b32 s24, v255, 25
	v_readlane_b32 s25, v255, 26
	v_readlane_b32 s26, v255, 27
	v_readlane_b32 s27, v255, 28
	v_readlane_b32 s28, v255, 29
	v_readlane_b32 s29, v255, 30
	v_readlane_b32 s30, v255, 31
	v_readlane_b32 s31, v255, 32
	v_readlane_b32 s33, v255, 33
	v_readlane_b32 s54, v255, 34
	v_readlane_b32 s64, v255, 35
	s_branch .LBB0_765

	.amdhsa_kernel _Z8mega_fwd4Args
		.amdhsa_group_segment_fixed_size 0
		.amdhsa_private_segment_fixed_size 0
		.amdhsa_kernarg_size 504
		.amdhsa_user_sgpr_count 2
		.amdhsa_user_sgpr_dispatch_ptr 0
		.amdhsa_user_sgpr_queue_ptr 0
		.amdhsa_user_sgpr_kernarg_segment_ptr 1
		.amdhsa_user_sgpr_dispatch_id 0
		.amdhsa_user_sgpr_kernarg_preload_length 0
		.amdhsa_user_sgpr_kernarg_preload_offset 0
		.amdhsa_user_sgpr_private_segment_size 0
		.amdhsa_uses_dynamic_stack 0
		.amdhsa_enable_private_segment 0
		.amdhsa_system_sgpr_workgroup_id_x 1
		.amdhsa_system_sgpr_workgroup_id_y 0
		.amdhsa_system_sgpr_workgroup_id_z 0
		.amdhsa_system_sgpr_workgroup_info 0
		.amdhsa_system_vgpr_workitem_id 0
		.amdhsa_next_free_vgpr 256
		.amdhsa_next_free_sgpr 102
		.amdhsa_accum_offset 256
		.amdhsa_reserve_vcc 1
		.amdhsa_float_round_mode_32 0
		.amdhsa_float_round_mode_16_64 0
		.amdhsa_float_denorm_mode_32 3
		.amdhsa_float_denorm_mode_16_64 3
		.amdhsa_dx10_clamp 1
		.amdhsa_ieee_mode 1
		.amdhsa_fp16_overflow 0
		.amdhsa_tg_split 0
		.amdhsa_exception_fp_ieee_invalid_op 0
		.amdhsa_exception_fp_denorm_src 0
		.amdhsa_exception_fp_ieee_div_zero 0
		.amdhsa_exception_fp_ieee_overflow 0
		.amdhsa_exception_fp_ieee_underflow 0
		.amdhsa_exception_fp_ieee_inexact 0
		.amdhsa_exception_int_div_zero 0
	.end_amdhsa_kernel

amdhsa.kernels:
  - .agpr_count:     0
    .args:
      - .offset:         0
        .size:           248
        .value_kind:     by_value
      - .offset:         248
        .size:           4
        .value_kind:     hidden_block_count_x
      - .offset:         252
        .size:           4
        .value_kind:     hidden_block_count_y
      - .offset:         256
        .size:           4
        .value_kind:     hidden_block_count_z
      - .offset:         260
        .size:           2
        .value_kind:     hidden_group_size_x
      - .offset:         262
        .size:           2
        .value_kind:     hidden_group_size_y
      - .offset:         264
        .size:           2
        .value_kind:     hidden_group_size_z
      - .offset:         266
        .size:           2
        .value_kind:     hidden_remainder_x
      - .offset:         268
        .size:           2
        .value_kind:     hidden_remainder_y
      - .offset:         270
        .size:           2
        .value_kind:     hidden_remainder_z
      - .offset:         288
        .size:           8
        .value_kind:     hidden_global_offset_x
      - .offset:         296
        .size:           8
        .value_kind:     hidden_global_offset_y
      - .offset:         304
        .size:           8
        .value_kind:     hidden_global_offset_z
      - .offset:         312
        .size:           2
        .value_kind:     hidden_grid_dims
      - .offset:         368
        .size:           4
        .value_kind:     hidden_dynamic_lds_size
    .group_segment_fixed_size: 0
    .kernarg_segment_align: 8
    .kernarg_segment_size: 504
    .language:       OpenCL C
    .language_version:
      - 2
      - 0
    .max_flat_workgroup_size: 512
    .name:           _Z8mega_fwd4Args
    .private_segment_fixed_size: 0
    .sgpr_count:     108
    .sgpr_spill_count: 87
    .symbol:         _Z8mega_fwd4Args.kd
    .uniform_work_group_size: 1
    .uses_dynamic_stack: false
    .vgpr_count:     256
    .vgpr_spill_count: 0
    .wavefront_size: 64
